# HG chunk item pairwise-score loop unrolled x2 with ping-pong registers (no copies)
# speedup vs baseline: 1.0063x; 1.0016x over previous
.LBB0_277:
	s_or_b64 exec, exec, s[16:17]
	v_lshlrev_b32_e32 v60, 2, v40
	v_readlane_b32 s0, v253, 50
	v_readlane_b32 s1, v253, 51
	v_readlane_b32 s2, v253, 52
	v_add_u32_e32 v83, s0, v60
	ds_read_b32 v61, v83
	v_add_u32_e32 v84, s1, v60
	v_add_u32_e32 v85, s2, v60
	v_readlane_b32 s4, v253, 53
	v_lshl_add_u32 v59, v54, 2, 0
	s_waitcnt lgkmcnt(0)
	v_fma_f32 v47, v47, v61, 0
	ds_read_b32 v61, v84
	v_add_u32_e32 v86, s4, v60
	s_waitcnt lgkmcnt(0)
	v_fmac_f32_e32 v47, v38, v61
	ds_read_b32 v38, v85
	s_waitcnt lgkmcnt(0)
	v_fmac_f32_e32 v47, v51, v38
	ds_read_b32 v38, v86
	s_waitcnt lgkmcnt(0)
	v_fmac_f32_e32 v47, v37, v38
	v_mul_f32_e32 v37, 0xbfb8aa3b, v47
	v_exp_f32_e32 v37, v37
	s_nop 0
	v_add_f32_e32 v37, 1.0, v37
	v_rcp_f32_e32 v37, v37
	s_nop 0
	v_mul_f32_e32 v37, v47, v37
	ds_write_b32 v59, v37 offset:24576
	v_lshlrev_b32_e32 v37, 2, v42
	v_add_u32_e32 v87, s0, v37
	ds_read_b32 v38, v87
	v_add_u32_e32 v88, s1, v37
	ds_read_b32 v47, v88
	v_add_u32_e32 v90, s4, v37
	v_add_u32_e32 v89, s2, v37
	ds_read_b32 v37, v90
	s_waitcnt lgkmcnt(2)
	v_fma_f32 v38, v50, v38, 0
	s_waitcnt lgkmcnt(1)
	v_fmac_f32_e32 v38, v48, v47
	ds_read_b32 v47, v89
	s_waitcnt lgkmcnt(0)
	v_fmac_f32_e32 v38, v53, v47
	v_fmac_f32_e32 v38, v46, v37
	v_mul_f32_e32 v37, 0xbfb8aa3b, v38
	v_exp_f32_e32 v37, v37
	s_nop 0
	v_add_f32_e32 v37, 1.0, v37
	v_rcp_f32_e32 v37, v37
	s_nop 0
	v_mul_f32_e32 v37, v38, v37
	ds_write_b32 v59, v37 offset:26624
	v_lshlrev_b32_e32 v37, 2, v44
	v_add_u32_e32 v91, s0, v37
	ds_read_b32 v38, v91
	v_add_u32_e32 v92, s1, v37
	ds_read_b32 v46, v92
	v_add_u32_e32 v94, s4, v37
	v_add_u32_e32 v93, s2, v37
	ds_read_b32 v37, v94
	s_waitcnt lgkmcnt(2)
	v_fma_f32 v38, v52, v38, 0
	s_waitcnt lgkmcnt(1)
	v_fmac_f32_e32 v38, v49, v46
	ds_read_b32 v46, v93
	s_or_b32 s4, s26, 16
	s_waitcnt lgkmcnt(0)
	v_fmac_f32_e32 v38, v58, v46
	v_fmac_f32_e32 v38, v39, v37
	v_mul_f32_e32 v37, 0xbfb8aa3b, v38
	v_exp_f32_e32 v37, v37
	s_nop 0
	v_add_f32_e32 v37, 1.0, v37
	v_rcp_f32_e32 v37, v37
	s_nop 0
	v_mul_f32_e32 v37, v38, v37
	ds_write_b32 v59, v37 offset:28672
	s_waitcnt vmcnt(0)
	s_and_saveexec_b64 s[0:1], s[10:11]
	s_cbranch_execz .LBB0_287
	v_add_u32_e32 v15, v32, v0
	v_mul_lo_u32 v14, v15, 48
	v_sub_u32_e32 v14, v54, v14
	v_add_u32_e32 v16, s4, v15
	v_ashrrev_i32_e32 v15, 31, v14
	v_lshl_add_u64 v[14:15], v[14:15], 1, s[34:35]
	v_cmp_lt_i32_e32 vcc, 2, v16
	v_mov_b32_e32 v65, 0
	v_mov_b32_e32 v57, 0
	v_mov_b32_e32 v64, 0
	s_and_saveexec_b64 s[16:17], vcc
	s_cbranch_execz .LBB0_280
	v_add_u32_e32 v17, -3, v16
	v_mad_u64_u32 v[18:19], s[18:19], v17, s69, v[14:15]
	global_load_ushort v64, v[18:19], off offset:384
	global_load_ushort v57, v[18:19], off
.LBB0_280:
	s_or_b64 exec, exec, s[16:17]
	v_cmp_lt_i32_e32 vcc, 1, v16
	v_mov_b32_e32 v66, 0
	s_and_saveexec_b64 s[16:17], vcc
	s_cbranch_execz .LBB0_282
	v_add_u32_e32 v17, -2, v16
	v_mad_u64_u32 v[18:19], s[18:19], v17, s69, v[14:15]
	global_load_ushort v66, v[18:19], off offset:384
	global_load_ushort v65, v[18:19], off
.LBB0_282:
	s_or_b64 exec, exec, s[16:17]
	v_cmp_lt_i32_e32 vcc, 0, v16
	v_mov_b32_e32 v69, 0
	v_mov_b32_e32 v67, 0
	v_mov_b32_e32 v68, 0
	s_and_saveexec_b64 s[16:17], vcc
	s_cbranch_execz .LBB0_284
	v_add_u32_e32 v17, -1, v16
	v_mad_u64_u32 v[18:19], s[18:19], v17, s69, v[14:15]
	global_load_ushort v68, v[18:19], off offset:384
	global_load_ushort v67, v[18:19], off

.LBB0_286:
	s_or_b64 exec, exec, s[16:17]
	v_mov_b64_e32 v[14:15], s[30:31]
	v_mad_i64_i32 v[18:19], s[16:17], v16, s69, v[14:15]
	global_load_dwordx4 v[14:17], v[18:19], off offset:1552
	s_nop 0
	global_load_dwordx4 v[18:21], v[18:19], off offset:1536
.LBB0_287:
	s_or_b64 exec, exec, s[0:1]
	s_and_saveexec_b64 s[0:1], s[14:15]
	s_cbranch_execz .LBB0_297
	v_add_u32_e32 v23, v36, v35
	v_mul_lo_u32 v22, v23, 48
	v_sub_u32_e32 v22, v34, v22
	v_add_u32_e32 v24, s4, v23
	v_ashrrev_i32_e32 v23, 31, v22
	v_lshl_add_u64 v[22:23], v[22:23], 1, s[34:35]
	v_cmp_lt_i32_e32 vcc, 2, v24
	v_mov_b32_e32 v73, 0
	v_mov_b32_e32 v71, 0
	v_mov_b32_e32 v72, 0
	s_and_saveexec_b64 s[16:17], vcc
	s_cbranch_execz .LBB0_290
	v_add_u32_e32 v25, -3, v24
	v_mad_u64_u32 v[26:27], s[4:5], v25, s69, v[22:23]
	global_load_ushort v72, v[26:27], off offset:384
	global_load_ushort v71, v[26:27], off

.LBB0_296:
	s_or_b64 exec, exec, s[16:17]
	v_mov_b64_e32 v[22:23], s[30:31]
	v_mad_i64_i32 v[26:27], s[4:5], v24, s69, v[22:23]
	global_load_dwordx4 v[22:25], v[26:27], off offset:1552
	s_nop 0
	global_load_dwordx4 v[26:29], v[26:27], off offset:1536
.LBB0_297:
	s_or_b64 exec, exec, s[0:1]
	s_or_b32 s4, s26, 13
	v_add_u32_e32 v37, s4, v75
	v_cmp_lt_i32_e32 vcc, -1, v37
	v_mov_b32_e32 v107, 0
	v_mov_b32_e32 v108, 0
	s_and_saveexec_b64 s[0:1], vcc
	s_cbranch_execz .LBB0_299
	v_mov_b64_e32 v[38:39], s[30:31]
	v_mad_u64_u32 v[38:39], s[16:17], v37, s69, v[38:39]
	s_lshl_b32 s72, s36, 1
	v_lshl_add_u64 v[38:39], v[38:39], 0, s[72:73]
	v_lshl_add_u64 v[38:39], v[40:41], 1, v[38:39]
	global_load_ushort v108, v[38:39], off offset:768

; #define LAS __attribute__((address_space(3)))
; __device__ __forceinline__ void hg_item_C(const Params& p, int l, int seg, int h, LAS float* sm, int tid, int lane, int wave) {
;     ...
;             for (int t = j; t < TS; ++t) {
;                 const f32x4 a0 = na0, a1 = na1, d0 = nd0, d1 = nd1;
;                 { const int tn = (t + 1 < TS) ? t + 1 : t, tn2 = (t + 2 < TS) ? t + 2 : TS - 1;
;                   na0 = *(const LAS f32x4*)(bf + tn * K + 8 * sl); na1 = *(const LAS f32x4*)(bf + tn * K + 8 * sl + 4);
;                   nd0 = *(const LAS f32x4*)(bf + 2048 + tn2 * K + 8 * sl); nd1 = *(const LAS f32x4*)(bf + 2048 + tn2 * K + 8 * sl + 4); }
;                 part[(t * 16 + j) * 16 + sl] = (a0.x * z0.x + a0.y * z0.y) + (a0.z * z0.z + a0.w * z0.w) + (a1.x * z1.x + a1.y * z1.y) + (a1.z * z1.z + a1.w * z1.w);
;                 z0 = z0 * d0; z1 = z1 * d1;
;             }
.LBB0_435:
	v_cmp_ne_u32_e32 vcc, 15, v109
	v_mov_b32_e32 v110, 0x780
	v_min_i32_e32 v118, 13, v109
	v_cndmask_b32_e32 v110, v110, v107, vcc
	v_lshl_add_u32 v114, v110, 2, v106
	v_lshl_add_u32 v122, v118, 9, v106
	s_waitcnt lgkmcnt(0)
	v_pk_mul_f32 v[42:43], v[26:27], v[42:43]
	v_pk_mul_f32 v[40:41], v[24:25], v[40:41]
	ds_read_b128 v[110:113], v114
	ds_read_b128 v[114:117], v114 offset:16
	ds_read_b128 v[118:121], v122 offset:9216
	ds_read_b128 v[122:125], v122 offset:9232
	v_pk_mov_b32 v[126:127], v[40:41], v[42:43] op_sel:[1,0]
	v_mov_b32_e32 v41, v43
	v_pk_mul_f32 v[38:39], v[22:23], v[38:39]
	v_pk_mul_f32 v[36:37], v[20:21], v[36:37]
	v_pk_add_f32 v[40:41], v[126:127], v[40:41]
	v_mov_b32_e32 v42, v38
	v_mov_b32_e32 v43, v36
	v_mov_b32_e32 v36, v39
	v_pk_add_f32 v[36:37], v[42:43], v[36:37]
	v_add_f32_e32 v38, v40, v41
	v_add_f32_e32 v37, v37, v38
	v_add_f32_e32 v36, v36, v37
	v_cmp_lt_i32_e32 vcc, 14, v109
	ds_write_b32 v108, v36
	v_pk_mul_f32 v[26:27], v[26:27], v[34:35]
	v_pk_mul_f32 v[24:25], v[24:25], v[32:33]
	v_pk_mul_f32 v[22:23], v[22:23], v[30:31]
	v_pk_mul_f32 v[20:21], v[20:21], v[28:29]
	v_add_u32_e32 v108, 0x400, v108
	v_add_u32_e32 v107, 0x80, v107
	v_add_u32_e32 v109, 1, v109
	s_or_b64 s[22:23], vcc, s[22:23]
	s_andn2_b64 exec, exec, s[22:23]
	s_cbranch_execz .Lmy_hgp1_done
	v_cmp_ne_u32_e32 vcc, 15, v109
	v_mov_b32_e32 v40, 0x780
	v_min_i32_e32 v32, 13, v109
	v_cndmask_b32_e32 v40, v40, v107, vcc
	v_lshl_add_u32 v36, v40, 2, v106
	v_lshl_add_u32 v28, v32, 9, v106
	s_waitcnt lgkmcnt(0)
	v_pk_mul_f32 v[112:113], v[26:27], v[112:113]
	v_pk_mul_f32 v[110:111], v[24:25], v[110:111]
	ds_read_b128 v[40:43], v36
	ds_read_b128 v[36:39], v36 offset:16
	ds_read_b128 v[32:35], v28 offset:9216
	ds_read_b128 v[28:31], v28 offset:9232
	v_pk_mov_b32 v[126:127], v[110:111], v[112:113] op_sel:[1,0]
	v_mov_b32_e32 v111, v113
	v_pk_mul_f32 v[116:117], v[22:23], v[116:117]
	v_pk_mul_f32 v[114:115], v[20:21], v[114:115]
	v_pk_add_f32 v[110:111], v[126:127], v[110:111]
	v_mov_b32_e32 v112, v116
	v_mov_b32_e32 v113, v114
	v_mov_b32_e32 v114, v117
	v_pk_add_f32 v[114:115], v[112:113], v[114:115]
	v_add_f32_e32 v116, v110, v111
	v_add_f32_e32 v115, v115, v116
	v_add_f32_e32 v114, v114, v115
	v_cmp_lt_i32_e32 vcc, 14, v109
	ds_write_b32 v108, v114
	v_pk_mul_f32 v[26:27], v[26:27], v[120:121]
	v_pk_mul_f32 v[24:25], v[24:25], v[118:119]
	v_pk_mul_f32 v[22:23], v[22:23], v[124:125]
	v_pk_mul_f32 v[20:21], v[20:21], v[122:123]
	v_add_u32_e32 v108, 0x400, v108
	v_add_u32_e32 v107, 0x80, v107
	v_add_u32_e32 v109, 1, v109
	s_or_b64 s[22:23], vcc, s[22:23]
	s_andn2_b64 exec, exec, s[22:23]
	s_cbranch_execnz .LBB0_435
.Lmy_hgp1_done:
.LBB0_436:
	s_or_b64 exec, exec, s[20:21]

.LBB0_598:
	s_or_b64 exec, exec, s[22:23]
	v_lshlrev_b32_e32 v57, 2, v18
	v_readlane_b32 s0, v253, 50
	v_readlane_b32 s1, v253, 51
	v_readlane_b32 s2, v253, 52
	v_add_u32_e32 v54, s0, v57
	ds_read_b32 v55, v54
	v_readlane_b32 s22, v253, 53
	v_lshl_add_u32 v53, v30, 2, 0
	s_or_b32 s36, s25, 0x60
	s_waitcnt lgkmcnt(0)
	v_fma_f32 v40, v40, v55, 0
	v_add_u32_e32 v55, s1, v57
	ds_read_b32 v56, v55
	s_waitcnt lgkmcnt(0)
	v_fmac_f32_e32 v40, v37, v56
	v_add_u32_e32 v56, s2, v57
	ds_read_b32 v37, v56
	v_add_u32_e32 v57, s22, v57
	s_waitcnt lgkmcnt(0)
	v_fmac_f32_e32 v40, v44, v37
	ds_read_b32 v37, v57
	s_waitcnt lgkmcnt(0)
	v_fmac_f32_e32 v40, v36, v37
	v_mul_f32_e32 v36, 0xbfb8aa3b, v40
	v_exp_f32_e32 v36, v36
	s_nop 0
	v_add_f32_e32 v36, 1.0, v36
	v_rcp_f32_e32 v36, v36
	s_nop 0
	v_mul_f32_e32 v36, v40, v36
	ds_write_b32 v53, v36 offset:55296
	v_lshlrev_b32_e32 v36, 2, v20
	v_add_u32_e32 v58, s0, v36
	ds_read_b32 v37, v58
	v_add_u32_e32 v59, s1, v36
	ds_read_b32 v40, v59
	v_add_u32_e32 v60, s2, v36
	s_waitcnt lgkmcnt(1)
	v_fma_f32 v37, v43, v37, 0
	s_waitcnt lgkmcnt(0)
	v_fmac_f32_e32 v37, v41, v40
	ds_read_b32 v40, v60
	s_waitcnt lgkmcnt(0)
	v_fmac_f32_e32 v37, v61, v40
	v_add_u32_e32 v61, s22, v36
	ds_read_b32 v36, v61
	s_waitcnt lgkmcnt(0)
	v_fmac_f32_e32 v37, v39, v36
	v_mul_f32_e32 v36, 0xbfb8aa3b, v37
	v_exp_f32_e32 v36, v36
	s_nop 0
	v_add_f32_e32 v36, 1.0, v36
	v_rcp_f32_e32 v36, v36
	s_nop 0
	v_mul_f32_e32 v36, v37, v36
	ds_write_b32 v53, v36 offset:57344
	v_lshlrev_b32_e32 v36, 2, v22
	v_add_u32_e32 v62, s0, v36
	ds_read_b32 v37, v62
	v_add_u32_e32 v63, s1, v36
	ds_read_b32 v39, v63
	v_add_u32_e32 v64, s2, v36
	s_waitcnt lgkmcnt(1)
	v_fma_f32 v37, v45, v37, 0
	s_waitcnt lgkmcnt(0)
	v_fmac_f32_e32 v37, v42, v39
	ds_read_b32 v39, v64
	s_waitcnt lgkmcnt(0)
	v_fmac_f32_e32 v37, v65, v39
	v_add_u32_e32 v65, s22, v36
	ds_read_b32 v36, v65
	s_waitcnt lgkmcnt(0)
	v_fmac_f32_e32 v37, v38, v36
	v_mul_f32_e32 v36, 0xbfb8aa3b, v37
	v_exp_f32_e32 v36, v36
	s_nop 0
	v_add_f32_e32 v36, 1.0, v36
	v_rcp_f32_e32 v36, v36
	s_nop 0
	v_mul_f32_e32 v36, v37, v36
	ds_write_b32 v53, v36 offset:59392
	s_waitcnt vmcnt(0)
	s_and_saveexec_b64 s[0:1], s[10:11]
	s_cbranch_execz .LBB0_608
	v_add_u32_e32 v7, v25, v24
	v_mul_lo_u32 v6, v7, 48
	v_sub_u32_e32 v6, v30, v6
	v_add_u32_e32 v8, s36, v7
	v_ashrrev_i32_e32 v7, 31, v6
	v_lshl_add_u64 v[6:7], v[6:7], 1, s[14:15]
	v_cmp_lt_i32_e32 vcc, 2, v8
	v_mov_b32_e32 v49, 0
	v_mov_b32_e32 v50, 0
	s_and_saveexec_b64 s[22:23], vcc
	s_cbranch_execz .LBB0_601
	v_add_u32_e32 v9, -3, v8
	v_mad_u64_u32 v[14:15], s[38:39], v9, s69, v[6:7]
	global_load_ushort v50, v[14:15], off offset:384

.LBB0_608:
	s_or_b64 exec, exec, s[0:1]
	s_and_saveexec_b64 s[0:1], s[12:13]
	s_cbranch_execz .LBB0_618
	v_add_u32_e32 v0, v28, v27
	v_mul_lo_u32 v2, v0, 48
	v_sub_u32_e32 v2, v26, v2
	v_add_u32_e32 v4, s36, v0
	v_ashrrev_i32_e32 v3, 31, v2
	v_lshl_add_u64 v[2:3], v[2:3], 1, s[14:15]
	v_cmp_lt_i32_e32 vcc, 2, v4
	v_mov_b32_e32 v31, 0
	v_mov_b32_e32 v48, 0
	s_and_saveexec_b64 s[22:23], vcc
	s_cbranch_execz .LBB0_611
	v_add_u32_e32 v0, -3, v4
	v_mad_u64_u32 v[10:11], s[36:37], v0, s69, v[2:3]
	global_load_ushort v48, v[10:11], off offset:384

.LBB0_617:
	s_or_b64 exec, exec, s[22:23]
	v_mov_b64_e32 v[2:3], s[20:21]
	v_mad_i64_i32 v[10:11], s[22:23], v4, s69, v[2:3]
	global_load_dwordx4 v[2:5], v[10:11], off offset:1552
	s_nop 0
	global_load_dwordx4 v[10:13], v[10:11], off offset:1536
.LBB0_618:
	s_or_b64 exec, exec, s[0:1]
	s_and_b32 s0, s25, 0x7fffff80
	s_or_b32 s22, s0, 0x5d
	v_add_u32_e32 v36, s22, v29
	v_cmp_lt_i32_e32 vcc, -1, v36
	v_mov_b32_e32 v85, 0
	v_mov_b32_e32 v95, 0
	s_and_saveexec_b64 s[0:1], vcc
	s_cbranch_execz .LBB0_620
	v_mov_b64_e32 v[38:39], s[20:21]
	v_mad_u64_u32 v[38:39], s[36:37], v36, s69, v[38:39]
	s_lshl_b32 s72, s24, 1
	v_lshl_add_u64 v[38:39], v[38:39], 0, s[72:73]
	v_lshl_add_u64 v[38:39], v[18:19], 1, v[38:39]
	global_load_ushort v95, v[38:39], off offset:768
